# MLP1 epilogues: bias folded into accumulator init (8 bias loads at tile head), 32 serialized load-wait-add steps removed
# speedup vs baseline: 1.0146x; 1.0143x over previous
.LBB0_110:
	s_lshl_b64 s[24:25], s[28:29], 13
	s_add_u32 s28, s34, s24
	s_addc_u32 s29, s35, s25
	s_ashr_i32 s31, s30, 31
	v_lshlrev_b32_e32 v138, 2, v196
	s_lshl_b64 s[24:25], s[30:31], 2
	v_or_b32_e32 v132, v186, v138
	s_add_u32 s34, s54, s24
	s_addc_u32 s35, s55, s25
	v_ashrrev_i32_e32 v133, 31, v132
	v_lshl_add_u64 v[132:133], v[132:133], 2, s[34:35]
	v_ashrrev_i32_e32 v185, 31, v184
	v_lshlrev_b64 v[140:141], 13, v[184:185]
	s_lshl_b64 s[30:31], s[30:31], 1
	v_ashrrev_i32_e32 v187, 31, v186
	v_mov_b32_e32 v139, v3
	s_add_i32 s56, s56, s76
	s_cmp_ge_i32 s56, s58
	v_mov_b32_e32 v2, v116
	v_mov_b32_e32 v116, v117
	v_mov_b32_e32 v117, v118
	v_max_f32_e32 v116, 0, v116
	v_max_f32_e32 v117, 0, v117
	v_max_f32_e32 v2, 0, v2
	v_mov_b32_e32 v118, v119
	v_pk_mul_f32 v[116:117], v[116:117], v[116:117]
	v_max_f32_e32 v118, 0, v118
	v_fma_mixlo_f16 v2, v2, v2, 0
	v_cvt_pk_f16_f32 v116, v116, v117
	v_pack_b32_f16 v134, v2, v116
	v_fma_mixlo_f16 v2, v118, v118, 0
	v_alignbit_b32 v135, v2, v116, 16
	v_mov_b32_e32 v2, v120
	v_mov_b32_e32 v116, v121
	v_mov_b32_e32 v117, v122
	v_max_f32_e32 v116, 0, v116
	v_max_f32_e32 v117, 0, v117
	v_max_f32_e32 v2, 0, v2
	v_mov_b32_e32 v118, v123
	v_pk_mul_f32 v[116:117], v[116:117], v[116:117]
	v_max_f32_e32 v118, 0, v118
	v_fma_mixlo_f16 v2, v2, v2, 0
	v_cvt_pk_f16_f32 v116, v116, v117
	v_pack_b32_f16 v136, v2, v116
	v_fma_mixlo_f16 v2, v118, v118, 0
	v_alignbit_b32 v137, v2, v116, 16
	v_lshl_add_u64 v[116:117], s[28:29], 0, v[140:141]
	v_lshl_add_u64 v[116:117], v[116:117], 0, s[30:31]
	v_lshlrev_b64 v[118:119], 1, v[186:187]
	v_lshl_add_u64 v[116:117], v[116:117], 0, v[118:119]
	v_lshlrev_b32_e32 v2, 4, v196
	v_permlane32_swap_b32_e32 v134, v136
	v_permlane32_swap_b32_e32 v135, v137
	v_lshl_add_u64 v[120:121], v[116:117], 0, v[2:3]
	v_lshl_add_u64 v[116:117], v[186:187], 0, v[138:139]
	global_store_dwordx4 v[120:121], v[134:137], off
	s_nop 1
	v_lshl_add_u64 v[116:117], v[116:117], 2, s[34:35]
	v_mov_b32_e32 v122, v124
	v_max_f32_e32 v124, 0, v122
	v_mov_b32_e32 v122, v125
	v_mov_b32_e32 v123, v126
	v_max_f32_e32 v122, 0, v122
	v_max_f32_e32 v123, 0, v123
	v_mov_b32_e32 v125, v127
	v_pk_mul_f32 v[122:123], v[122:123], v[122:123]
	v_max_f32_e32 v125, 0, v125
	v_fma_mixlo_f16 v124, v124, v124, 0
	v_cvt_pk_f16_f32 v123, v122, v123
	v_pack_b32_f16 v122, v124, v123
	v_fma_mixlo_f16 v124, v125, v125, 0
	v_alignbit_b32 v123, v124, v123, 16
	v_mov_b32_e32 v124, v128
	v_max_f32_e32 v128, 0, v124
	v_mov_b32_e32 v124, v129
	v_mov_b32_e32 v125, v130
	v_max_f32_e32 v124, 0, v124
	v_max_f32_e32 v125, 0, v125
	v_mov_b32_e32 v126, v131
	v_max_f32_e32 v126, 0, v126
	v_pk_mul_f32 v[124:125], v[124:125], v[124:125]
	v_fma_mixlo_f16 v127, v128, v128, 0
	v_cvt_pk_f16_f32 v125, v124, v125
	v_fma_mixlo_f16 v126, v126, v126, 0
	v_pack_b32_f16 v124, v127, v125
	v_alignbit_b32 v125, v126, v125, 16
	s_nop 0
	v_permlane32_swap_b32_e32 v122, v124
	v_permlane32_swap_b32_e32 v123, v125
	global_store_dwordx4 v[120:121], v[122:125], off offset:32
	s_nop 1
	v_max_f32_e32 v122, 0, v100
	v_mov_b32_e32 v100, v101
	v_mov_b32_e32 v101, v102
	v_mov_b32_e32 v102, v103
	v_fma_mixlo_f16 v103, v122, v122, 0
	v_max_f32_e32 v100, 0, v100
	v_max_f32_e32 v101, 0, v101
	v_max_f32_e32 v102, 0, v102
	v_pk_mul_f32 v[100:101], v[100:101], v[100:101]
	v_fma_mixlo_f16 v102, v102, v102, 0
	v_cvt_pk_f16_f32 v101, v100, v101
	v_pack_b32_f16 v100, v103, v101
	v_alignbit_b32 v101, v102, v101, 16
	v_mov_b32_e32 v102, v104
	v_max_f32_e32 v104, 0, v102
	v_mov_b32_e32 v102, v105
	v_mov_b32_e32 v103, v106
	v_max_f32_e32 v102, 0, v102
	v_max_f32_e32 v103, 0, v103
	v_mov_b32_e32 v105, v107
	v_pk_mul_f32 v[102:103], v[102:103], v[102:103]
	v_max_f32_e32 v105, 0, v105
	v_fma_mixlo_f16 v104, v104, v104, 0
	v_cvt_pk_f16_f32 v103, v102, v103
	v_pack_b32_f16 v102, v104, v103
	v_fma_mixlo_f16 v104, v105, v105, 0
	v_alignbit_b32 v103, v104, v103, 16
	v_permlane32_swap_b32_e32 v100, v102
	s_nop 0
	v_permlane32_swap_b32_e32 v101, v103
	global_store_dwordx4 v[120:121], v[100:103], off offset:64
	s_nop 1
	v_mov_b32_e32 v100, v108
	v_max_f32_e32 v104, 0, v100
	v_mov_b32_e32 v100, v109
	v_mov_b32_e32 v101, v110
	v_max_f32_e32 v100, 0, v100
	v_max_f32_e32 v101, 0, v101
	v_mov_b32_e32 v102, v111
	v_max_f32_e32 v102, 0, v102
	v_pk_mul_f32 v[100:101], v[100:101], v[100:101]
	v_fma_mixlo_f16 v103, v104, v104, 0
	v_cvt_pk_f16_f32 v101, v100, v101
	v_fma_mixlo_f16 v102, v102, v102, 0
	v_pack_b32_f16 v100, v103, v101
	v_alignbit_b32 v101, v102, v101, 16
	v_mov_b32_e32 v102, v112
	v_max_f32_e32 v106, 0, v102
	v_mov_b32_e32 v102, v113
	v_mov_b32_e32 v103, v114
	v_max_f32_e32 v102, 0, v102
	v_max_f32_e32 v103, 0, v103
	v_mov_b32_e32 v104, v115
	v_max_f32_e32 v104, 0, v104
	v_pk_mul_f32 v[102:103], v[102:103], v[102:103]
	v_fma_mixlo_f16 v105, v106, v106, 0
	v_cvt_pk_f16_f32 v103, v102, v103
	v_fma_mixlo_f16 v104, v104, v104, 0
	v_pack_b32_f16 v102, v105, v103
	v_alignbit_b32 v103, v104, v103, 16
	s_nop 0
	v_permlane32_swap_b32_e32 v100, v102
	v_permlane32_swap_b32_e32 v101, v103
	global_store_dwordx4 v[120:121], v[100:103], off offset:96
	s_nop 1
	s_nop 1
	v_or_b32_e32 v100, 32, v184
	v_ashrrev_i32_e32 v101, 31, v100
	v_lshlrev_b64 v[104:105], 13, v[100:101]
	v_max_f32_e32 v100, 0, v84
	v_mov_b32_e32 v84, v85
	v_mov_b32_e32 v85, v86
	v_mov_b32_e32 v86, v87
	v_fma_mixlo_f16 v87, v100, v100, 0
	v_max_f32_e32 v84, 0, v84
	v_max_f32_e32 v85, 0, v85
	v_max_f32_e32 v86, 0, v86
	v_pk_mul_f32 v[84:85], v[84:85], v[84:85]
	v_fma_mixlo_f16 v86, v86, v86, 0
	v_cvt_pk_f16_f32 v85, v84, v85
	v_pack_b32_f16 v84, v87, v85
	v_alignbit_b32 v85, v86, v85, 16
	v_mov_b32_e32 v86, v88
	v_max_f32_e32 v88, 0, v86
	v_mov_b32_e32 v86, v89
	v_mov_b32_e32 v87, v90
	v_max_f32_e32 v86, 0, v86
	v_max_f32_e32 v87, 0, v87
	v_mov_b32_e32 v89, v91
	v_pk_mul_f32 v[86:87], v[86:87], v[86:87]
	v_max_f32_e32 v89, 0, v89
	v_fma_mixlo_f16 v88, v88, v88, 0
	v_cvt_pk_f16_f32 v87, v86, v87
	v_pack_b32_f16 v86, v88, v87
	v_fma_mixlo_f16 v88, v89, v89, 0
	v_alignbit_b32 v87, v88, v87, 16
	v_lshl_add_u64 v[88:89], s[28:29], 0, v[104:105]
	v_lshl_add_u64 v[88:89], v[88:89], 0, s[30:31]
	v_lshl_add_u64 v[88:89], v[88:89], 0, v[118:119]
	v_permlane32_swap_b32_e32 v84, v86
	v_permlane32_swap_b32_e32 v85, v87
	v_lshl_add_u64 v[88:89], v[88:89], 0, v[2:3]
	global_store_dwordx4 v[88:89], v[84:87], off
	s_nop 1
	v_mov_b32_e32 v84, v92
	v_max_f32_e32 v90, 0, v84
	v_mov_b32_e32 v84, v93
	v_mov_b32_e32 v85, v94
	v_mov_b32_e32 v86, v95
	v_fma_mixlo_f16 v87, v90, v90, 0
	v_max_f32_e32 v84, 0, v84
	v_max_f32_e32 v85, 0, v85
	v_max_f32_e32 v86, 0, v86
	v_pk_mul_f32 v[84:85], v[84:85], v[84:85]
	v_fma_mixlo_f16 v86, v86, v86, 0
	v_cvt_pk_f16_f32 v85, v84, v85
	v_pack_b32_f16 v84, v87, v85
	v_alignbit_b32 v85, v86, v85, 16
	v_mov_b32_e32 v86, v96
	v_max_f32_e32 v90, 0, v86
	v_mov_b32_e32 v86, v97
	v_mov_b32_e32 v87, v98
	v_max_f32_e32 v86, 0, v86
	v_max_f32_e32 v87, 0, v87
	v_mov_b32_e32 v91, v99
	v_pk_mul_f32 v[86:87], v[86:87], v[86:87]
	v_max_f32_e32 v91, 0, v91
	v_fma_mixlo_f16 v90, v90, v90, 0
	v_cvt_pk_f16_f32 v87, v86, v87
	v_pack_b32_f16 v86, v90, v87
	v_fma_mixlo_f16 v90, v91, v91, 0
	v_alignbit_b32 v87, v90, v87, 16
	v_permlane32_swap_b32_e32 v84, v86
	s_nop 0
	v_permlane32_swap_b32_e32 v85, v87
	global_store_dwordx4 v[88:89], v[84:87], off offset:32
	s_nop 1
	v_max_f32_e32 v84, 0, v68
	v_mov_b32_e32 v68, v69
	v_mov_b32_e32 v69, v70
	v_mov_b32_e32 v70, v71
	v_fma_mixlo_f16 v71, v84, v84, 0
	v_max_f32_e32 v68, 0, v68
	v_max_f32_e32 v69, 0, v69
	v_max_f32_e32 v70, 0, v70
	v_pk_mul_f32 v[68:69], v[68:69], v[68:69]
	v_fma_mixlo_f16 v70, v70, v70, 0
	v_cvt_pk_f16_f32 v69, v68, v69
	v_pack_b32_f16 v68, v71, v69
	v_alignbit_b32 v69, v70, v69, 16
	v_mov_b32_e32 v70, v72
	v_max_f32_e32 v72, 0, v70
	v_mov_b32_e32 v70, v73
	v_mov_b32_e32 v71, v74
	v_max_f32_e32 v70, 0, v70
	v_max_f32_e32 v71, 0, v71
	v_mov_b32_e32 v73, v75
	v_pk_mul_f32 v[70:71], v[70:71], v[70:71]
	v_max_f32_e32 v73, 0, v73
	v_fma_mixlo_f16 v72, v72, v72, 0
	v_cvt_pk_f16_f32 v71, v70, v71
	v_pack_b32_f16 v70, v72, v71
	v_fma_mixlo_f16 v72, v73, v73, 0
	v_alignbit_b32 v71, v72, v71, 16
	v_permlane32_swap_b32_e32 v68, v70
	s_nop 0
	v_permlane32_swap_b32_e32 v69, v71
	global_store_dwordx4 v[88:89], v[68:71], off offset:64
	s_nop 1
	v_mov_b32_e32 v68, v76
	v_max_f32_e32 v72, 0, v68
	v_mov_b32_e32 v68, v77
	v_mov_b32_e32 v69, v78
	v_max_f32_e32 v68, 0, v68
	v_max_f32_e32 v69, 0, v69
	v_mov_b32_e32 v70, v79
	v_max_f32_e32 v70, 0, v70
	v_pk_mul_f32 v[68:69], v[68:69], v[68:69]
	v_fma_mixlo_f16 v71, v72, v72, 0
	v_cvt_pk_f16_f32 v69, v68, v69
	v_fma_mixlo_f16 v70, v70, v70, 0
	v_pack_b32_f16 v68, v71, v69
	v_alignbit_b32 v69, v70, v69, 16
	v_mov_b32_e32 v70, v80
	v_max_f32_e32 v74, 0, v70
	v_mov_b32_e32 v70, v81
	v_mov_b32_e32 v71, v82
	v_max_f32_e32 v70, 0, v70
	v_max_f32_e32 v71, 0, v71
	v_mov_b32_e32 v72, v83
	v_max_f32_e32 v72, 0, v72
	v_pk_mul_f32 v[70:71], v[70:71], v[70:71]
	v_fma_mixlo_f16 v73, v74, v74, 0
	v_cvt_pk_f16_f32 v71, v70, v71
	v_fma_mixlo_f16 v72, v72, v72, 0
	v_pack_b32_f16 v70, v73, v71
	v_alignbit_b32 v71, v72, v71, 16
	s_nop 0
	v_permlane32_swap_b32_e32 v68, v70
	v_permlane32_swap_b32_e32 v69, v71
	global_store_dwordx4 v[88:89], v[68:71], off offset:96
	s_nop 1
	s_nop 1
	v_or_b32_e32 v68, 64, v184
	v_ashrrev_i32_e32 v69, 31, v68
	v_lshlrev_b64 v[72:73], 13, v[68:69]
	v_max_f32_e32 v68, 0, v52
	v_mov_b32_e32 v52, v53
	v_mov_b32_e32 v53, v54
	v_mov_b32_e32 v54, v55
	v_fma_mixlo_f16 v55, v68, v68, 0
	v_max_f32_e32 v52, 0, v52
	v_max_f32_e32 v53, 0, v53
	v_max_f32_e32 v54, 0, v54
	v_pk_mul_f32 v[52:53], v[52:53], v[52:53]
	v_fma_mixlo_f16 v54, v54, v54, 0
	v_cvt_pk_f16_f32 v53, v52, v53
	v_pack_b32_f16 v52, v55, v53
	v_alignbit_b32 v53, v54, v53, 16
	v_mov_b32_e32 v54, v56
	v_max_f32_e32 v56, 0, v54
	v_mov_b32_e32 v54, v57
	v_mov_b32_e32 v55, v58
	v_max_f32_e32 v54, 0, v54
	v_max_f32_e32 v55, 0, v55
	v_mov_b32_e32 v57, v59
	v_pk_mul_f32 v[54:55], v[54:55], v[54:55]
	v_max_f32_e32 v57, 0, v57
	v_fma_mixlo_f16 v56, v56, v56, 0
	v_cvt_pk_f16_f32 v55, v54, v55
	v_pack_b32_f16 v54, v56, v55
	v_fma_mixlo_f16 v56, v57, v57, 0
	v_alignbit_b32 v55, v56, v55, 16
	v_lshl_add_u64 v[56:57], s[28:29], 0, v[72:73]
	v_lshl_add_u64 v[56:57], v[56:57], 0, s[30:31]
	v_lshl_add_u64 v[56:57], v[56:57], 0, v[118:119]
	v_permlane32_swap_b32_e32 v52, v54
	v_permlane32_swap_b32_e32 v53, v55
	v_lshl_add_u64 v[56:57], v[56:57], 0, v[2:3]
	global_store_dwordx4 v[56:57], v[52:55], off
	s_nop 1
	v_mov_b32_e32 v52, v60
	v_max_f32_e32 v58, 0, v52
	v_mov_b32_e32 v52, v61
	v_mov_b32_e32 v53, v62
	v_mov_b32_e32 v54, v63
	v_fma_mixlo_f16 v55, v58, v58, 0
	v_max_f32_e32 v52, 0, v52
	v_max_f32_e32 v53, 0, v53
	v_max_f32_e32 v54, 0, v54
	v_pk_mul_f32 v[52:53], v[52:53], v[52:53]
	v_fma_mixlo_f16 v54, v54, v54, 0
	v_cvt_pk_f16_f32 v53, v52, v53
	v_pack_b32_f16 v52, v55, v53
	v_alignbit_b32 v53, v54, v53, 16
	v_mov_b32_e32 v54, v64
	v_max_f32_e32 v58, 0, v54
	v_mov_b32_e32 v54, v65
	v_mov_b32_e32 v55, v66
	v_max_f32_e32 v54, 0, v54
	v_max_f32_e32 v55, 0, v55
	v_mov_b32_e32 v59, v67
	v_pk_mul_f32 v[54:55], v[54:55], v[54:55]
	v_max_f32_e32 v59, 0, v59
	v_fma_mixlo_f16 v58, v58, v58, 0
	v_cvt_pk_f16_f32 v55, v54, v55
	v_pack_b32_f16 v54, v58, v55
	v_fma_mixlo_f16 v58, v59, v59, 0
	v_alignbit_b32 v55, v58, v55, 16
	v_permlane32_swap_b32_e32 v52, v54
	s_nop 0
	v_permlane32_swap_b32_e32 v53, v55
	global_store_dwordx4 v[56:57], v[52:55], off offset:32
	s_nop 1
	v_max_f32_e32 v52, 0, v36
	v_mov_b32_e32 v36, v37
	v_mov_b32_e32 v37, v38
	v_mov_b32_e32 v38, v39
	v_fma_mixlo_f16 v39, v52, v52, 0
	v_max_f32_e32 v36, 0, v36
	v_max_f32_e32 v37, 0, v37
	v_max_f32_e32 v38, 0, v38
	v_pk_mul_f32 v[36:37], v[36:37], v[36:37]
	v_fma_mixlo_f16 v38, v38, v38, 0
	v_cvt_pk_f16_f32 v37, v36, v37
	v_pack_b32_f16 v36, v39, v37
	v_alignbit_b32 v37, v38, v37, 16
	v_mov_b32_e32 v38, v40
	v_max_f32_e32 v40, 0, v38
	v_mov_b32_e32 v38, v41
	v_mov_b32_e32 v39, v42
	v_max_f32_e32 v38, 0, v38
	v_max_f32_e32 v39, 0, v39
	v_mov_b32_e32 v41, v43
	v_pk_mul_f32 v[38:39], v[38:39], v[38:39]
	v_max_f32_e32 v41, 0, v41
	v_fma_mixlo_f16 v40, v40, v40, 0
	v_cvt_pk_f16_f32 v39, v38, v39
	v_pack_b32_f16 v38, v40, v39
	v_fma_mixlo_f16 v40, v41, v41, 0
	v_alignbit_b32 v39, v40, v39, 16
	v_permlane32_swap_b32_e32 v36, v38
	s_nop 0
	v_permlane32_swap_b32_e32 v37, v39
	global_store_dwordx4 v[56:57], v[36:39], off offset:64
	s_nop 1
	v_mov_b32_e32 v36, v44
	v_max_f32_e32 v40, 0, v36
	v_mov_b32_e32 v36, v45
	v_mov_b32_e32 v37, v46
	v_max_f32_e32 v36, 0, v36
	v_max_f32_e32 v37, 0, v37
	v_mov_b32_e32 v38, v47
	v_max_f32_e32 v38, 0, v38
	v_pk_mul_f32 v[36:37], v[36:37], v[36:37]
	v_fma_mixlo_f16 v39, v40, v40, 0
	v_cvt_pk_f16_f32 v37, v36, v37
	v_fma_mixlo_f16 v38, v38, v38, 0
	v_pack_b32_f16 v36, v39, v37
	v_alignbit_b32 v37, v38, v37, 16
	v_mov_b32_e32 v38, v48
	v_max_f32_e32 v42, 0, v38
	v_mov_b32_e32 v38, v49
	v_mov_b32_e32 v39, v50
	v_max_f32_e32 v38, 0, v38
	v_max_f32_e32 v39, 0, v39
	v_mov_b32_e32 v40, v51
	v_max_f32_e32 v40, 0, v40
	v_pk_mul_f32 v[38:39], v[38:39], v[38:39]
	v_fma_mixlo_f16 v41, v42, v42, 0
	v_cvt_pk_f16_f32 v39, v38, v39
	v_fma_mixlo_f16 v40, v40, v40, 0
	v_pack_b32_f16 v38, v41, v39
	v_alignbit_b32 v39, v40, v39, 16
	s_nop 0
	v_permlane32_swap_b32_e32 v36, v38
	v_permlane32_swap_b32_e32 v37, v39
	global_store_dwordx4 v[56:57], v[36:39], off offset:96
	s_nop 1
	s_nop 1
	v_or_b32_e32 v36, 0x60, v184
	v_ashrrev_i32_e32 v37, 31, v36
	v_lshlrev_b64 v[40:41], 13, v[36:37]
	v_max_f32_e32 v36, 0, v20
	v_mov_b32_e32 v20, v21
	v_mov_b32_e32 v21, v22
	v_mov_b32_e32 v22, v23
	v_fma_mixlo_f16 v23, v36, v36, 0
	v_max_f32_e32 v20, 0, v20
	v_max_f32_e32 v21, 0, v21
	v_max_f32_e32 v22, 0, v22
	v_pk_mul_f32 v[20:21], v[20:21], v[20:21]
	v_fma_mixlo_f16 v22, v22, v22, 0
	v_cvt_pk_f16_f32 v21, v20, v21
	v_pack_b32_f16 v20, v23, v21
	v_alignbit_b32 v21, v22, v21, 16
	v_mov_b32_e32 v22, v24
	v_max_f32_e32 v24, 0, v22
	v_mov_b32_e32 v22, v25
	v_mov_b32_e32 v23, v26
	v_max_f32_e32 v22, 0, v22
	v_max_f32_e32 v23, 0, v23
	v_mov_b32_e32 v25, v27
	v_pk_mul_f32 v[22:23], v[22:23], v[22:23]
	v_max_f32_e32 v25, 0, v25
	v_fma_mixlo_f16 v24, v24, v24, 0
	v_cvt_pk_f16_f32 v23, v22, v23
	v_pack_b32_f16 v22, v24, v23
	v_fma_mixlo_f16 v24, v25, v25, 0
	v_alignbit_b32 v23, v24, v23, 16
	v_lshl_add_u64 v[24:25], s[28:29], 0, v[40:41]
	v_lshl_add_u64 v[24:25], v[24:25], 0, s[30:31]
	v_lshl_add_u64 v[24:25], v[24:25], 0, v[118:119]
	v_permlane32_swap_b32_e32 v20, v22
	v_permlane32_swap_b32_e32 v21, v23
	v_lshl_add_u64 v[24:25], v[24:25], 0, v[2:3]
	global_store_dwordx4 v[24:25], v[20:23], off
	s_nop 1
	v_mov_b32_e32 v2, v28
	v_mov_b32_e32 v20, v29
	v_mov_b32_e32 v21, v30
	v_max_f32_e32 v20, 0, v20
	v_max_f32_e32 v21, 0, v21
	v_max_f32_e32 v2, 0, v2
	v_mov_b32_e32 v22, v31
	v_pk_mul_f32 v[20:21], v[20:21], v[20:21]
	v_max_f32_e32 v22, 0, v22
	v_fma_mixlo_f16 v2, v2, v2, 0
	v_cvt_pk_f16_f32 v21, v20, v21
	v_pack_b32_f16 v20, v2, v21
	v_fma_mixlo_f16 v2, v22, v22, 0
	v_alignbit_b32 v21, v2, v21, 16
	v_mov_b32_e32 v22, v33
	v_mov_b32_e32 v23, v34
	v_mov_b32_e32 v2, v32
	v_max_f32_e32 v22, 0, v22
	v_max_f32_e32 v23, 0, v23
	v_max_f32_e32 v2, 0, v2
	v_mov_b32_e32 v26, v35
	v_pk_mul_f32 v[22:23], v[22:23], v[22:23]
	v_max_f32_e32 v26, 0, v26
	v_fma_mixlo_f16 v2, v2, v2, 0
	v_cvt_pk_f16_f32 v23, v22, v23
	v_pack_b32_f16 v22, v2, v23
	v_fma_mixlo_f16 v2, v26, v26, 0
	v_alignbit_b32 v23, v2, v23, 16
	v_permlane32_swap_b32_e32 v20, v22
	s_nop 0
	v_permlane32_swap_b32_e32 v21, v23
	global_store_dwordx4 v[24:25], v[20:23], off offset:32
	s_nop 1
	v_mov_b32_e32 v2, v4
	v_mov_b32_e32 v4, v5
	v_mov_b32_e32 v5, v6
	v_mov_b32_e32 v6, v7
	v_max_f32_e32 v4, 0, v4
	v_max_f32_e32 v5, 0, v5
	v_max_f32_e32 v2, 0, v2
	v_pk_mul_f32 v[4:5], v[4:5], v[4:5]
	v_max_f32_e32 v6, 0, v6
	v_fma_mixlo_f16 v2, v2, v2, 0
	v_cvt_pk_f16_f32 v5, v4, v5
	v_pack_b32_f16 v4, v2, v5
	v_fma_mixlo_f16 v2, v6, v6, 0
	v_alignbit_b32 v5, v2, v5, 16
	v_mov_b32_e32 v6, v9
	v_mov_b32_e32 v7, v10
	v_mov_b32_e32 v2, v8
	v_max_f32_e32 v6, 0, v6
	v_max_f32_e32 v7, 0, v7
	v_max_f32_e32 v2, 0, v2
	v_mov_b32_e32 v8, v11
	v_pk_mul_f32 v[6:7], v[6:7], v[6:7]
	v_max_f32_e32 v8, 0, v8
	v_fma_mixlo_f16 v2, v2, v2, 0
	v_cvt_pk_f16_f32 v7, v6, v7
	v_pack_b32_f16 v6, v2, v7
	v_fma_mixlo_f16 v2, v8, v8, 0
	v_alignbit_b32 v7, v2, v7, 16
	v_permlane32_swap_b32_e32 v4, v6
	s_nop 0
	v_permlane32_swap_b32_e32 v5, v7
	global_store_dwordx4 v[24:25], v[4:7], off offset:64
	s_nop 1
	v_mov_b32_e32 v2, v12
	v_mov_b32_e32 v4, v13
	v_mov_b32_e32 v5, v14
	v_max_f32_e32 v4, 0, v4
	v_max_f32_e32 v5, 0, v5
	v_max_f32_e32 v2, 0, v2
	v_mov_b32_e32 v6, v15
	v_pk_mul_f32 v[4:5], v[4:5], v[4:5]
	v_max_f32_e32 v6, 0, v6
	v_fma_mixlo_f16 v2, v2, v2, 0
	v_cvt_pk_f16_f32 v5, v4, v5
	v_pack_b32_f16 v4, v2, v5
	v_fma_mixlo_f16 v2, v6, v6, 0
	v_alignbit_b32 v5, v2, v5, 16
	v_mov_b32_e32 v2, v16
	v_mov_b32_e32 v6, v17
	v_mov_b32_e32 v7, v18
	v_max_f32_e32 v6, 0, v6
	v_max_f32_e32 v7, 0, v7
	v_max_f32_e32 v2, 0, v2
	v_mov_b32_e32 v8, v19
	v_pk_mul_f32 v[6:7], v[6:7], v[6:7]
	v_max_f32_e32 v8, 0, v8
	v_fma_mixlo_f16 v2, v2, v2, 0
	v_cvt_pk_f16_f32 v7, v6, v7
	v_pack_b32_f16 v6, v2, v7
	v_fma_mixlo_f16 v2, v8, v8, 0
	v_alignbit_b32 v7, v2, v7, 16
	v_permlane32_swap_b32_e32 v4, v6
	s_nop 0
	v_permlane32_swap_b32_e32 v5, v7
	global_store_dwordx4 v[24:25], v[4:7], off offset:96
	s_nop 1
	s_cbranch_scc1 .LBB0_127

.LBB0_115:
	v_mov_b32_e32 v6, v200
	s_lshl_b32 s24, s25, 4
	s_sub_i32 s24, s56, s24
	v_ashrrev_i32_e32 v8, 6, v6
	v_bfe_u32 v4, v6, 2, 4
	v_lshlrev_b32_e32 v5, 5, v8
	v_and_b32_e32 v7, 63, v6
	v_or_b32_e32 v9, v5, v4
	s_lshl_b32 s30, s24, 8
	v_bfe_u32 v176, v200, 6, 2
	v_bfe_u32 v177, v200, 5, 1
	v_lshlrev_b32_e32 v176, 6, v176
	v_lshl_or_b32 v176, v177, 2, v176
	v_add_u32_e32 v176, s30, v176
	v_lshlrev_b32_e32 v176, 2, v176
	global_load_dwordx4 v[144:147], v176, s[54:55]
	global_load_dwordx4 v[148:151], v176, s[54:55] offset:32
	global_load_dwordx4 v[152:155], v176, s[54:55] offset:64
	global_load_dwordx4 v[156:159], v176, s[54:55] offset:96
	global_load_dwordx4 v[160:163], v176, s[54:55] offset:128
	global_load_dwordx4 v[164:167], v176, s[54:55] offset:160
	global_load_dwordx4 v[168:171], v176, s[54:55] offset:192
	global_load_dwordx4 v[172:175], v176, s[54:55] offset:224
	v_lshrrev_b32_e32 v2, 4, v6
	v_add_u32_e32 v10, s36, v9
	v_or_b32_e32 v16, 16, v9
	v_add_u32_e32 v14, s30, v9
	v_lshlrev_b32_e32 v9, 4, v7
	v_xor_b32_e32 v2, v2, v6
	v_ashrrev_i32_e32 v11, 31, v10
	v_add_u32_e32 v12, s36, v16
	v_lshl_or_b32 v185, v8, 11, v9
	v_lshlrev_b64 v[10:11], 11, v[10:11]
	v_lshlrev_b32_e32 v2, 4, v2
	v_ashrrev_i32_e32 v13, 31, v12
	v_add_u32_e32 v9, 16, v185
	v_lshl_add_u64 v[10:11], s[42:43], 0, v[10:11]
	v_and_b32_e32 v2, 48, v2
	v_lshlrev_b64 v[12:13], 11, v[12:13]
	v_ashrrev_i32_e32 v15, 31, v14
	v_add_u32_e32 v16, s30, v16
	v_readfirstlane_b32 s24, v9
	v_add_u32_e32 v18, 0x400, v9
	v_lshl_add_u64 v[10:11], v[10:11], 0, v[2:3]
	v_lshl_add_u64 v[12:13], s[42:43], 0, v[12:13]
	v_lshlrev_b64 v[14:15], 11, v[14:15]
	v_ashrrev_i32_e32 v17, 31, v16
	s_mov_b32 m0, s24
	v_readfirstlane_b32 s24, v18
	v_add_u32_e32 v18, 0x4000, v9
	v_lshl_add_u64 v[12:13], v[12:13], 0, v[2:3]
	v_lshl_add_u64 v[14:15], s[44:45], 0, v[14:15]
	v_lshlrev_b64 v[16:17], 11, v[16:17]
	global_load_lds_dwordx4 v[10:11], off
	s_mov_b32 m0, s24
	v_readfirstlane_b32 s24, v18
	v_add_u32_e32 v18, 0x4400, v9
	v_lshl_add_u64 v[14:15], v[14:15], 0, v[2:3]
	v_lshl_add_u64 v[16:17], s[44:45], 0, v[16:17]
	global_load_lds_dwordx4 v[12:13], off
	s_mov_b32 m0, s24
	v_readfirstlane_b32 s24, v18
	v_add_u32_e32 v20, 0x8000, v9
	v_lshl_add_u64 v[16:17], v[16:17], 0, v[2:3]
	global_load_lds_dwordx4 v[14:15], off
	s_mov_b32 m0, s24
	v_readfirstlane_b32 s24, v20
	v_add_u32_e32 v20, 0x8400, v9
	global_load_lds_dwordx4 v[16:17], off
	v_lshl_add_u64 v[18:19], v[10:11], 0, 64
	s_mov_b32 m0, s24
	v_readfirstlane_b32 s24, v20
	v_add_u32_e32 v20, 0xc000, v9
	global_load_lds_dwordx4 v[18:19], off
	v_lshl_add_u64 v[18:19], v[12:13], 0, 64
	s_mov_b32 m0, s24
	v_readfirstlane_b32 s24, v20
	v_add_u32_e32 v9, 0xc400, v9
	global_load_lds_dwordx4 v[18:19], off
	v_lshl_add_u64 v[18:19], v[14:15], 0, 64
	s_mov_b32 m0, s24
	v_readfirstlane_b32 s24, v9
	global_load_lds_dwordx4 v[18:19], off
	s_mov_b32 m0, s24
	s_add_i32 s24, 16, 0x10000
	v_add_u32_e32 v9, s24, v185
	v_lshl_add_u64 v[18:19], v[16:17], 0, 64
	v_readfirstlane_b32 s24, v9
	global_load_lds_dwordx4 v[18:19], off
	v_lshl_add_u64 v[10:11], v[10:11], 0, s[92:93]
	s_mov_b32 m0, s24
	s_nop 0
	global_load_lds_dwordx4 v[10:11], off
	v_lshl_add_u64 v[10:11], v[12:13], 0, s[92:93]
	v_add_u32_e32 v12, 0x400, v9
	s_nop 0
	v_readfirstlane_b32 s24, v12
	v_add_u32_e32 v12, 0x4000, v9
	s_mov_b32 m0, s24
	v_readfirstlane_b32 s24, v12
	v_add_u32_e32 v9, 0x4400, v9
	global_load_lds_dwordx4 v[10:11], off
	v_lshl_add_u64 v[10:11], v[14:15], 0, s[92:93]
	s_mov_b32 m0, s24
	v_readfirstlane_b32 s24, v9
	global_load_lds_dwordx4 v[10:11], off
	v_lshl_add_u64 v[10:11], v[16:17], 0, s[92:93]
	s_mov_b32 m0, s24
	v_readfirstlane_b32 s24, v6
	global_load_lds_dwordx4 v[10:11], off
	s_waitcnt vmcnt(8)
	s_and_b32 s31, s24, 0xffffff00
	s_cmpk_lg_i32 s31, 0x100
	s_barrier
	s_cbranch_scc1 .LBB0_117
	s_barrier
.LBB0_117:
	v_lshrrev_b32_e32 v9, 30, v8
	v_add_u32_e32 v9, v8, v9
	v_ashrrev_i32_e32 v9, 2, v9
	v_mul_i32_i24_e32 v10, 4, v9
	v_sub_u32_e32 v8, v8, v10
	v_and_b32_e32 v10, 31, v6
	v_lshlrev_b32_e32 v186, 6, v8
	v_lshrrev_b32_e32 v196, 5, v7
	v_lshrrev_b32_e32 v7, 2, v6
	v_bfe_u32 v6, v6, 2, 2
	v_or_b32_e32 v8, v186, v10
	v_lshlrev_b32_e32 v197, 6, v8
	v_bitop3_b32 v6, v196, v6, 2 bitop3:0x36
	v_or_b32_e32 v8, 16, v4
	s_lshl_b32 s31, s56, 8
	v_lshlrev_b32_e32 v199, 4, v6
	v_or_b32_e32 v6, s31, v8
	v_add_u32_e32 v6, v6, v5
	s_lshl_b32 s25, s25, 12
	v_bitop3_b32 v7, v196, v7, 3 bitop3:0x78
	v_subrev_u32_e32 v6, s25, v6
	v_lshlrev_b32_e32 v198, 4, v7
	v_ashrrev_i32_e32 v7, 31, v6
	v_lshlrev_b64 v[6:7], 11, v[6:7]
	v_or_b32_e32 v6, v6, v2
	v_lshl_add_u64 v[188:189], s[48:49], 0, v[6:7]
	v_or_b32_e32 v6, s31, v4
	v_add_u32_e32 v6, v6, v5
	v_subrev_u32_e32 v6, s25, v6
	v_ashrrev_i32_e32 v7, 31, v6
	v_lshlrev_b64 v[6:7], 11, v[6:7]
	v_or_b32_e32 v6, v6, v2
	v_lshl_add_u64 v[190:191], s[48:49], 0, v[6:7]
	v_add3_u32 v6, v8, s36, v5
	v_add3_u32 v4, v4, s36, v5
	v_ashrrev_i32_e32 v7, 31, v6
	v_ashrrev_i32_e32 v5, 31, v4
	v_lshlrev_b64 v[6:7], 11, v[6:7]
	v_lshlrev_b64 v[4:5], 11, v[4:5]
	v_lshl_or_b32 v184, v9, 7, v10
	v_or_b32_e32 v6, v6, v2
	v_or_b32_e32 v4, v4, v2
	v_mov_b32_e32 v116, v144
	v_lshlrev_b32_e32 v187, 6, v184
	v_lshl_add_u64 v[192:193], s[50:51], 0, v[6:7]
	v_lshl_add_u64 v[194:195], s[50:51], 0, v[4:5]
	s_mov_b32 s25, 0x18000
	s_mov_b32 s31, 0
	s_mov_b64 s[36:37], 0
	s_mov_b32 s57, 0
	v_mov_b32_e32 v117, v145
	v_mov_b32_e32 v118, v146
	v_mov_b32_e32 v119, v147
	v_mov_b32_e32 v120, v148
	v_mov_b32_e32 v121, v149
	v_mov_b32_e32 v122, v150
	v_mov_b32_e32 v123, v151
	v_mov_b32_e32 v124, v152
	v_mov_b32_e32 v125, v153
	v_mov_b32_e32 v126, v154
	v_mov_b32_e32 v127, v155
	v_mov_b32_e32 v128, v156
	v_mov_b32_e32 v129, v157
	v_mov_b32_e32 v130, v158
	v_mov_b32_e32 v131, v159
	v_mov_b32_e32 v100, v160
	v_mov_b32_e32 v101, v161
	v_mov_b32_e32 v102, v162
	v_mov_b32_e32 v103, v163
	v_mov_b32_e32 v104, v164
	v_mov_b32_e32 v105, v165
	v_mov_b32_e32 v106, v166
	v_mov_b32_e32 v107, v167
	v_mov_b32_e32 v108, v168
	v_mov_b32_e32 v109, v169
	v_mov_b32_e32 v110, v170
	v_mov_b32_e32 v111, v171
	v_mov_b32_e32 v112, v172
	v_mov_b32_e32 v113, v173
	v_mov_b32_e32 v114, v174
	v_mov_b32_e32 v115, v175
	v_mov_b32_e32 v84, v144
	v_mov_b32_e32 v85, v145
	v_mov_b32_e32 v86, v146
	v_mov_b32_e32 v87, v147
	v_mov_b32_e32 v88, v148
	v_mov_b32_e32 v89, v149
	v_mov_b32_e32 v90, v150
	v_mov_b32_e32 v91, v151
	v_mov_b32_e32 v92, v152
	v_mov_b32_e32 v93, v153
	v_mov_b32_e32 v94, v154
	v_mov_b32_e32 v95, v155
	v_mov_b32_e32 v96, v156
	v_mov_b32_e32 v97, v157
	v_mov_b32_e32 v98, v158
	v_mov_b32_e32 v99, v159
	v_mov_b32_e32 v68, v160
	v_mov_b32_e32 v69, v161
	v_mov_b32_e32 v70, v162
	v_mov_b32_e32 v71, v163
	v_mov_b32_e32 v72, v164
	v_mov_b32_e32 v73, v165
	v_mov_b32_e32 v74, v166
	v_mov_b32_e32 v75, v167
	v_mov_b32_e32 v76, v168
	v_mov_b32_e32 v77, v169
	v_mov_b32_e32 v78, v170
	v_mov_b32_e32 v79, v171
	v_mov_b32_e32 v80, v172
	v_mov_b32_e32 v81, v173
	v_mov_b32_e32 v82, v174
	v_mov_b32_e32 v83, v175
	v_mov_b32_e32 v52, v144
	v_mov_b32_e32 v53, v145
	v_mov_b32_e32 v54, v146
	v_mov_b32_e32 v55, v147
	v_mov_b32_e32 v56, v148
	v_mov_b32_e32 v57, v149
	v_mov_b32_e32 v58, v150
	v_mov_b32_e32 v59, v151
	v_mov_b32_e32 v60, v152
	v_mov_b32_e32 v61, v153
	v_mov_b32_e32 v62, v154
	v_mov_b32_e32 v63, v155
	v_mov_b32_e32 v64, v156
	v_mov_b32_e32 v65, v157
	v_mov_b32_e32 v66, v158
	v_mov_b32_e32 v67, v159
	v_mov_b32_e32 v36, v160
	v_mov_b32_e32 v37, v161
	v_mov_b32_e32 v38, v162
	v_mov_b32_e32 v39, v163
	v_mov_b32_e32 v40, v164
	v_mov_b32_e32 v41, v165
	v_mov_b32_e32 v42, v166
	v_mov_b32_e32 v43, v167
	v_mov_b32_e32 v44, v168
	v_mov_b32_e32 v45, v169
	v_mov_b32_e32 v46, v170
	v_mov_b32_e32 v47, v171
	v_mov_b32_e32 v48, v172
	v_mov_b32_e32 v49, v173
	v_mov_b32_e32 v50, v174
	v_mov_b32_e32 v51, v175
	v_mov_b32_e32 v20, v144
	v_mov_b32_e32 v21, v145
	v_mov_b32_e32 v22, v146
	v_mov_b32_e32 v23, v147
	v_mov_b32_e32 v24, v148
	v_mov_b32_e32 v25, v149
	v_mov_b32_e32 v26, v150
	v_mov_b32_e32 v27, v151
	v_mov_b32_e32 v28, v152
	v_mov_b32_e32 v29, v153
	v_mov_b32_e32 v30, v154
	v_mov_b32_e32 v31, v155
	v_mov_b32_e32 v32, v156
	v_mov_b32_e32 v33, v157
	v_mov_b32_e32 v34, v158
	v_mov_b32_e32 v35, v159
	v_mov_b32_e32 v4, v160
	v_mov_b32_e32 v5, v161
	v_mov_b32_e32 v6, v162
	v_mov_b32_e32 v7, v163
	v_mov_b32_e32 v8, v164
	v_mov_b32_e32 v9, v165
	v_mov_b32_e32 v10, v166
	v_mov_b32_e32 v11, v167
	v_mov_b32_e32 v12, v168
	v_mov_b32_e32 v13, v169
	v_mov_b32_e32 v14, v170
	v_mov_b32_e32 v15, v171
	v_mov_b32_e32 v16, v172
	v_mov_b32_e32 v17, v173
	v_mov_b32_e32 v18, v174
	v_mov_b32_e32 v19, v175
	s_branch .LBB0_119

.LBB0_724:
	s_lshl_b64 s[28:29], s[28:29], 13
	s_add_u32 s28, s34, s28
	s_addc_u32 s29, s35, s29
	s_ashr_i32 s31, s30, 31
	v_lshlrev_b32_e32 v138, 2, v182
	s_lshl_b64 s[34:35], s[30:31], 2
	v_or_b32_e32 v132, v180, v138
	s_add_u32 s34, s24, s34
	s_addc_u32 s35, s25, s35
	v_ashrrev_i32_e32 v133, 31, v132
	v_lshl_add_u64 v[132:133], v[132:133], 2, s[34:35]
	v_ashrrev_i32_e32 v1, 31, v0
	v_lshlrev_b64 v[140:141], 13, v[0:1]
	s_lshl_b64 s[30:31], s[30:31], 1
	v_ashrrev_i32_e32 v181, 31, v180
	v_mov_b32_e32 v139, v3
	s_add_i32 s54, s54, s76
	s_cmp_ge_i32 s54, s58
	s_mov_b64 s[56:57], 0x1000
	v_mov_b32_e32 v2, v117
	v_mov_b32_e32 v1, v116
	v_max_f32_e32 v116, 0, v2
	v_mov_b32_e32 v2, v118
	v_max_f32_e32 v117, 0, v2
	v_max_f32_e32 v1, 0, v1
	v_mov_b32_e32 v2, v119
	v_pk_mul_f32 v[116:117], v[116:117], v[116:117]
	v_max_f32_e32 v2, 0, v2
	v_fma_mixlo_f16 v1, v1, v1, 0
	v_cvt_pk_f16_f32 v116, v116, v117
	v_pack_b32_f16 v134, v1, v116
	v_fma_mixlo_f16 v1, v2, v2, 0
	v_alignbit_b32 v135, v1, v116, 16
	v_mov_b32_e32 v2, v121
	v_mov_b32_e32 v1, v120
	v_max_f32_e32 v116, 0, v2
	v_mov_b32_e32 v2, v122
	v_max_f32_e32 v117, 0, v2
	v_max_f32_e32 v1, 0, v1
	v_mov_b32_e32 v2, v123
	v_pk_mul_f32 v[116:117], v[116:117], v[116:117]
	v_max_f32_e32 v2, 0, v2
	v_fma_mixlo_f16 v1, v1, v1, 0
	v_cvt_pk_f16_f32 v116, v116, v117
	v_pack_b32_f16 v136, v1, v116
	v_fma_mixlo_f16 v1, v2, v2, 0
	v_alignbit_b32 v137, v1, v116, 16
	v_lshl_add_u64 v[116:117], s[28:29], 0, v[140:141]
	v_lshl_add_u64 v[116:117], v[116:117], 0, s[30:31]
	v_lshlrev_b64 v[118:119], 1, v[180:181]
	v_lshl_add_u64 v[116:117], v[116:117], 0, v[118:119]
	v_lshlrev_b32_e32 v2, 4, v182
	v_permlane32_swap_b32_e32 v134, v136
	v_permlane32_swap_b32_e32 v135, v137
	v_lshl_add_u64 v[120:121], v[116:117], 0, v[2:3]
	v_lshl_add_u64 v[116:117], v[180:181], 0, v[138:139]
	global_store_dwordx4 v[120:121], v[134:137], off
	s_nop 1
	v_lshl_add_u64 v[116:117], v[116:117], 2, s[34:35]
	v_mov_b32_e32 v122, v125
	v_mov_b32_e32 v123, v126
	v_mov_b32_e32 v1, v124
	v_max_f32_e32 v122, 0, v122
	v_max_f32_e32 v123, 0, v123
	v_max_f32_e32 v1, 0, v1
	v_mov_b32_e32 v124, v127
	v_pk_mul_f32 v[122:123], v[122:123], v[122:123]
	v_max_f32_e32 v124, 0, v124
	v_fma_mixlo_f16 v1, v1, v1, 0
	v_cvt_pk_f16_f32 v123, v122, v123
	v_pack_b32_f16 v122, v1, v123
	v_fma_mixlo_f16 v1, v124, v124, 0
	v_alignbit_b32 v123, v1, v123, 16
	v_mov_b32_e32 v1, v128
	v_mov_b32_e32 v124, v129
	v_mov_b32_e32 v125, v130
	v_max_f32_e32 v124, 0, v124
	v_max_f32_e32 v125, 0, v125
	v_max_f32_e32 v1, 0, v1
	v_mov_b32_e32 v126, v131
	v_pk_mul_f32 v[124:125], v[124:125], v[124:125]
	v_max_f32_e32 v126, 0, v126
	v_fma_mixlo_f16 v1, v1, v1, 0
	v_cvt_pk_f16_f32 v125, v124, v125
	v_pack_b32_f16 v124, v1, v125
	v_fma_mixlo_f16 v1, v126, v126, 0
	v_alignbit_b32 v125, v1, v125, 16
	v_permlane32_swap_b32_e32 v122, v124
	s_nop 0
	v_permlane32_swap_b32_e32 v123, v125
	global_store_dwordx4 v[120:121], v[122:125], off offset:32
	s_nop 1
	v_mov_b32_e32 v1, v100
	v_mov_b32_e32 v100, v101
	v_mov_b32_e32 v101, v102
	v_mov_b32_e32 v102, v103
	v_max_f32_e32 v100, 0, v100
	v_max_f32_e32 v101, 0, v101
	v_max_f32_e32 v1, 0, v1
	v_pk_mul_f32 v[100:101], v[100:101], v[100:101]
	v_max_f32_e32 v102, 0, v102
	v_fma_mixlo_f16 v1, v1, v1, 0
	v_cvt_pk_f16_f32 v101, v100, v101
	v_pack_b32_f16 v100, v1, v101
	v_fma_mixlo_f16 v1, v102, v102, 0
	v_alignbit_b32 v101, v1, v101, 16
	v_mov_b32_e32 v102, v105
	v_mov_b32_e32 v103, v106
	v_mov_b32_e32 v1, v104
	v_max_f32_e32 v102, 0, v102
	v_max_f32_e32 v103, 0, v103
	v_max_f32_e32 v1, 0, v1
	v_mov_b32_e32 v104, v107
	v_pk_mul_f32 v[102:103], v[102:103], v[102:103]
	v_max_f32_e32 v104, 0, v104
	v_fma_mixlo_f16 v1, v1, v1, 0
	v_cvt_pk_f16_f32 v103, v102, v103
	v_pack_b32_f16 v102, v1, v103
	v_fma_mixlo_f16 v1, v104, v104, 0
	v_alignbit_b32 v103, v1, v103, 16
	v_permlane32_swap_b32_e32 v100, v102
	s_nop 0
	v_permlane32_swap_b32_e32 v101, v103
	global_store_dwordx4 v[120:121], v[100:103], off offset:64
	s_nop 1
	v_mov_b32_e32 v1, v108
	v_mov_b32_e32 v100, v109
	v_mov_b32_e32 v101, v110
	v_max_f32_e32 v100, 0, v100
	v_max_f32_e32 v101, 0, v101
	v_max_f32_e32 v1, 0, v1
	v_mov_b32_e32 v102, v111
	v_pk_mul_f32 v[100:101], v[100:101], v[100:101]
	v_max_f32_e32 v102, 0, v102
	v_fma_mixlo_f16 v1, v1, v1, 0
	v_cvt_pk_f16_f32 v101, v100, v101
	v_pack_b32_f16 v100, v1, v101
	v_fma_mixlo_f16 v1, v102, v102, 0
	v_alignbit_b32 v101, v1, v101, 16
	v_mov_b32_e32 v1, v112
	v_mov_b32_e32 v102, v113
	v_mov_b32_e32 v103, v114
	v_max_f32_e32 v102, 0, v102
	v_max_f32_e32 v103, 0, v103
	v_max_f32_e32 v1, 0, v1
	v_mov_b32_e32 v104, v115
	v_pk_mul_f32 v[102:103], v[102:103], v[102:103]
	v_max_f32_e32 v104, 0, v104
	v_fma_mixlo_f16 v1, v1, v1, 0
	v_cvt_pk_f16_f32 v103, v102, v103
	v_pack_b32_f16 v102, v1, v103
	v_fma_mixlo_f16 v1, v104, v104, 0
	v_alignbit_b32 v103, v1, v103, 16
	v_permlane32_swap_b32_e32 v100, v102
	s_nop 0
	v_permlane32_swap_b32_e32 v101, v103
	global_store_dwordx4 v[120:121], v[100:103], off offset:96
	s_nop 1
	s_nop 1
	v_or_b32_e32 v100, 32, v0
	v_ashrrev_i32_e32 v101, 31, v100
	v_lshlrev_b64 v[104:105], 13, v[100:101]
	v_mov_b32_e32 v1, v84
	v_mov_b32_e32 v84, v85
	v_mov_b32_e32 v85, v86
	v_mov_b32_e32 v86, v87
	v_max_f32_e32 v84, 0, v84
	v_max_f32_e32 v85, 0, v85
	v_max_f32_e32 v1, 0, v1
	v_pk_mul_f32 v[84:85], v[84:85], v[84:85]
	v_max_f32_e32 v86, 0, v86
	v_fma_mixlo_f16 v1, v1, v1, 0
	v_cvt_pk_f16_f32 v85, v84, v85
	v_pack_b32_f16 v84, v1, v85
	v_fma_mixlo_f16 v1, v86, v86, 0
	v_alignbit_b32 v85, v1, v85, 16
	v_mov_b32_e32 v86, v89
	v_mov_b32_e32 v87, v90
	v_mov_b32_e32 v1, v88
	v_max_f32_e32 v86, 0, v86
	v_max_f32_e32 v87, 0, v87
	v_max_f32_e32 v1, 0, v1
	v_mov_b32_e32 v88, v91
	v_pk_mul_f32 v[86:87], v[86:87], v[86:87]
	v_max_f32_e32 v88, 0, v88
	v_fma_mixlo_f16 v1, v1, v1, 0
	v_cvt_pk_f16_f32 v87, v86, v87
	v_pack_b32_f16 v86, v1, v87
	v_fma_mixlo_f16 v1, v88, v88, 0
	v_lshl_add_u64 v[88:89], s[28:29], 0, v[104:105]
	v_lshl_add_u64 v[88:89], v[88:89], 0, s[30:31]
	v_alignbit_b32 v87, v1, v87, 16
	v_lshl_add_u64 v[88:89], v[88:89], 0, v[118:119]
	v_permlane32_swap_b32_e32 v84, v86
	v_permlane32_swap_b32_e32 v85, v87
	v_lshl_add_u64 v[88:89], v[88:89], 0, v[2:3]
	global_store_dwordx4 v[88:89], v[84:87], off
	s_nop 1
	v_mov_b32_e32 v1, v92
	v_mov_b32_e32 v84, v93
	v_mov_b32_e32 v85, v94
	v_max_f32_e32 v84, 0, v84
	v_max_f32_e32 v85, 0, v85
	v_max_f32_e32 v1, 0, v1
	v_mov_b32_e32 v86, v95
	v_pk_mul_f32 v[84:85], v[84:85], v[84:85]
	v_max_f32_e32 v86, 0, v86
	v_fma_mixlo_f16 v1, v1, v1, 0
	v_cvt_pk_f16_f32 v85, v84, v85
	v_pack_b32_f16 v84, v1, v85
	v_fma_mixlo_f16 v1, v86, v86, 0
	v_alignbit_b32 v85, v1, v85, 16
	v_mov_b32_e32 v86, v97
	v_mov_b32_e32 v87, v98
	v_mov_b32_e32 v1, v96
	v_max_f32_e32 v86, 0, v86
	v_max_f32_e32 v87, 0, v87
	v_max_f32_e32 v1, 0, v1
	v_mov_b32_e32 v90, v99
	v_pk_mul_f32 v[86:87], v[86:87], v[86:87]
	v_max_f32_e32 v90, 0, v90
	v_fma_mixlo_f16 v1, v1, v1, 0
	v_cvt_pk_f16_f32 v87, v86, v87
	v_pack_b32_f16 v86, v1, v87
	v_fma_mixlo_f16 v1, v90, v90, 0
	v_alignbit_b32 v87, v1, v87, 16
	v_permlane32_swap_b32_e32 v84, v86
	s_nop 0
	v_permlane32_swap_b32_e32 v85, v87
	global_store_dwordx4 v[88:89], v[84:87], off offset:32
	s_nop 1
	v_mov_b32_e32 v1, v68
	v_mov_b32_e32 v68, v69
	v_mov_b32_e32 v69, v70
	v_mov_b32_e32 v70, v71
	v_max_f32_e32 v68, 0, v68
	v_max_f32_e32 v69, 0, v69
	v_max_f32_e32 v1, 0, v1
	v_pk_mul_f32 v[68:69], v[68:69], v[68:69]
	v_max_f32_e32 v70, 0, v70
	v_fma_mixlo_f16 v1, v1, v1, 0
	v_cvt_pk_f16_f32 v69, v68, v69
	v_pack_b32_f16 v68, v1, v69
	v_fma_mixlo_f16 v1, v70, v70, 0
	v_alignbit_b32 v69, v1, v69, 16
	v_mov_b32_e32 v70, v73
	v_mov_b32_e32 v71, v74
	v_mov_b32_e32 v1, v72
	v_max_f32_e32 v70, 0, v70
	v_max_f32_e32 v71, 0, v71
	v_max_f32_e32 v1, 0, v1
	v_mov_b32_e32 v72, v75
	v_pk_mul_f32 v[70:71], v[70:71], v[70:71]
	v_max_f32_e32 v72, 0, v72
	v_fma_mixlo_f16 v1, v1, v1, 0
	v_cvt_pk_f16_f32 v71, v70, v71
	v_pack_b32_f16 v70, v1, v71
	v_fma_mixlo_f16 v1, v72, v72, 0
	v_alignbit_b32 v71, v1, v71, 16
	v_permlane32_swap_b32_e32 v68, v70
	s_nop 0
	v_permlane32_swap_b32_e32 v69, v71
	global_store_dwordx4 v[88:89], v[68:71], off offset:64
	s_nop 1
	v_mov_b32_e32 v1, v76
	v_mov_b32_e32 v68, v77
	v_mov_b32_e32 v69, v78
	v_max_f32_e32 v68, 0, v68
	v_max_f32_e32 v69, 0, v69
	v_max_f32_e32 v1, 0, v1
	v_mov_b32_e32 v70, v79
	v_pk_mul_f32 v[68:69], v[68:69], v[68:69]
	v_max_f32_e32 v70, 0, v70
	v_fma_mixlo_f16 v1, v1, v1, 0
	v_cvt_pk_f16_f32 v69, v68, v69
	v_pack_b32_f16 v68, v1, v69
	v_fma_mixlo_f16 v1, v70, v70, 0
	v_alignbit_b32 v69, v1, v69, 16
	v_mov_b32_e32 v1, v80
	v_mov_b32_e32 v70, v81
	v_mov_b32_e32 v71, v82
	v_max_f32_e32 v70, 0, v70
	v_max_f32_e32 v71, 0, v71
	v_max_f32_e32 v1, 0, v1
	v_mov_b32_e32 v72, v83
	v_pk_mul_f32 v[70:71], v[70:71], v[70:71]
	v_max_f32_e32 v72, 0, v72
	v_fma_mixlo_f16 v1, v1, v1, 0
	v_cvt_pk_f16_f32 v71, v70, v71
	v_pack_b32_f16 v70, v1, v71
	v_fma_mixlo_f16 v1, v72, v72, 0
	v_alignbit_b32 v71, v1, v71, 16
	v_permlane32_swap_b32_e32 v68, v70
	s_nop 0
	v_permlane32_swap_b32_e32 v69, v71
	global_store_dwordx4 v[88:89], v[68:71], off offset:96
	s_nop 1
	s_nop 1
	v_or_b32_e32 v68, 64, v0
	v_ashrrev_i32_e32 v69, 31, v68
	v_lshlrev_b64 v[72:73], 13, v[68:69]
	v_or_b32_e32 v0, 0x60, v0
	v_mov_b32_e32 v1, v52
	v_mov_b32_e32 v52, v53
	v_mov_b32_e32 v53, v54
	v_mov_b32_e32 v54, v55
	v_max_f32_e32 v52, 0, v52
	v_max_f32_e32 v53, 0, v53
	v_max_f32_e32 v1, 0, v1
	v_pk_mul_f32 v[52:53], v[52:53], v[52:53]
	v_max_f32_e32 v54, 0, v54
	v_fma_mixlo_f16 v1, v1, v1, 0
	v_cvt_pk_f16_f32 v53, v52, v53
	v_pack_b32_f16 v52, v1, v53
	v_fma_mixlo_f16 v1, v54, v54, 0
	v_alignbit_b32 v53, v1, v53, 16
	v_mov_b32_e32 v54, v57
	v_mov_b32_e32 v55, v58
	v_mov_b32_e32 v1, v56
	v_max_f32_e32 v54, 0, v54
	v_max_f32_e32 v55, 0, v55
	v_max_f32_e32 v1, 0, v1
	v_mov_b32_e32 v56, v59
	v_pk_mul_f32 v[54:55], v[54:55], v[54:55]
	v_max_f32_e32 v56, 0, v56
	v_fma_mixlo_f16 v1, v1, v1, 0
	v_cvt_pk_f16_f32 v55, v54, v55
	v_pack_b32_f16 v54, v1, v55
	v_fma_mixlo_f16 v1, v56, v56, 0
	v_lshl_add_u64 v[56:57], s[28:29], 0, v[72:73]
	v_lshl_add_u64 v[56:57], v[56:57], 0, s[30:31]
	v_alignbit_b32 v55, v1, v55, 16
	v_lshl_add_u64 v[56:57], v[56:57], 0, v[118:119]
	v_permlane32_swap_b32_e32 v52, v54
	v_permlane32_swap_b32_e32 v53, v55
	v_lshl_add_u64 v[56:57], v[56:57], 0, v[2:3]
	global_store_dwordx4 v[56:57], v[52:55], off
	s_nop 1
	v_mov_b32_e32 v1, v60
	v_mov_b32_e32 v52, v61
	v_mov_b32_e32 v53, v62
	v_max_f32_e32 v52, 0, v52
	v_max_f32_e32 v53, 0, v53
	v_max_f32_e32 v1, 0, v1
	v_mov_b32_e32 v54, v63
	v_pk_mul_f32 v[52:53], v[52:53], v[52:53]
	v_max_f32_e32 v54, 0, v54
	v_fma_mixlo_f16 v1, v1, v1, 0
	v_cvt_pk_f16_f32 v53, v52, v53
	v_pack_b32_f16 v52, v1, v53
	v_fma_mixlo_f16 v1, v54, v54, 0
	v_alignbit_b32 v53, v1, v53, 16
	v_mov_b32_e32 v54, v65
	v_mov_b32_e32 v55, v66
	v_mov_b32_e32 v1, v64
	v_max_f32_e32 v54, 0, v54
	v_max_f32_e32 v55, 0, v55
	v_max_f32_e32 v1, 0, v1
	v_mov_b32_e32 v58, v67
	v_pk_mul_f32 v[54:55], v[54:55], v[54:55]
	v_max_f32_e32 v58, 0, v58
	v_fma_mixlo_f16 v1, v1, v1, 0
	v_cvt_pk_f16_f32 v55, v54, v55
	v_pack_b32_f16 v54, v1, v55
	v_fma_mixlo_f16 v1, v58, v58, 0
	v_alignbit_b32 v55, v1, v55, 16
	v_permlane32_swap_b32_e32 v52, v54
	s_nop 0
	v_permlane32_swap_b32_e32 v53, v55
	global_store_dwordx4 v[56:57], v[52:55], off offset:32
	s_nop 1
	v_mov_b32_e32 v1, v36
	v_mov_b32_e32 v36, v37
	v_mov_b32_e32 v37, v38
	v_mov_b32_e32 v38, v39
	v_max_f32_e32 v36, 0, v36
	v_max_f32_e32 v37, 0, v37
	v_max_f32_e32 v1, 0, v1
	v_pk_mul_f32 v[36:37], v[36:37], v[36:37]
	v_max_f32_e32 v38, 0, v38
	v_fma_mixlo_f16 v1, v1, v1, 0
	v_cvt_pk_f16_f32 v37, v36, v37
	v_pack_b32_f16 v36, v1, v37
	v_fma_mixlo_f16 v1, v38, v38, 0
	v_alignbit_b32 v37, v1, v37, 16
	v_mov_b32_e32 v38, v41
	v_mov_b32_e32 v39, v42
	v_mov_b32_e32 v1, v40
	v_max_f32_e32 v38, 0, v38
	v_max_f32_e32 v39, 0, v39
	v_max_f32_e32 v1, 0, v1
	v_mov_b32_e32 v40, v43
	v_pk_mul_f32 v[38:39], v[38:39], v[38:39]
	v_max_f32_e32 v40, 0, v40
	v_fma_mixlo_f16 v1, v1, v1, 0
	v_cvt_pk_f16_f32 v39, v38, v39
	v_pack_b32_f16 v38, v1, v39
	v_fma_mixlo_f16 v1, v40, v40, 0
	v_alignbit_b32 v39, v1, v39, 16
	v_permlane32_swap_b32_e32 v36, v38
	s_nop 0
	v_permlane32_swap_b32_e32 v37, v39
	global_store_dwordx4 v[56:57], v[36:39], off offset:64
	s_nop 1
	v_mov_b32_e32 v1, v44
	v_mov_b32_e32 v36, v45
	v_mov_b32_e32 v37, v46
	v_max_f32_e32 v36, 0, v36
	v_max_f32_e32 v37, 0, v37
	v_max_f32_e32 v1, 0, v1
	v_mov_b32_e32 v38, v47
	v_pk_mul_f32 v[36:37], v[36:37], v[36:37]
	v_max_f32_e32 v38, 0, v38
	v_fma_mixlo_f16 v1, v1, v1, 0
	v_cvt_pk_f16_f32 v37, v36, v37
	v_pack_b32_f16 v36, v1, v37
	v_fma_mixlo_f16 v1, v38, v38, 0
	v_alignbit_b32 v37, v1, v37, 16
	v_mov_b32_e32 v1, v48
	v_mov_b32_e32 v38, v49
	v_mov_b32_e32 v39, v50
	v_max_f32_e32 v38, 0, v38
	v_max_f32_e32 v39, 0, v39
	v_max_f32_e32 v1, 0, v1
	v_mov_b32_e32 v40, v51
	v_pk_mul_f32 v[38:39], v[38:39], v[38:39]
	v_max_f32_e32 v40, 0, v40
	v_fma_mixlo_f16 v1, v1, v1, 0
	v_cvt_pk_f16_f32 v39, v38, v39
	v_pack_b32_f16 v38, v1, v39
	v_fma_mixlo_f16 v1, v40, v40, 0
	v_alignbit_b32 v39, v1, v39, 16
	v_permlane32_swap_b32_e32 v36, v38
	s_nop 0
	v_permlane32_swap_b32_e32 v37, v39
	global_store_dwordx4 v[56:57], v[36:39], off offset:96
	s_nop 1
	v_ashrrev_i32_e32 v1, 31, v0
	v_lshlrev_b64 v[0:1], 13, v[0:1]
	v_lshl_add_u64 v[0:1], s[28:29], 0, v[0:1]
	v_lshl_add_u64 v[0:1], v[0:1], 0, s[30:31]
	v_lshl_add_u64 v[0:1], v[0:1], 0, v[118:119]
	v_lshl_add_u64 v[0:1], v[0:1], 0, v[2:3]
	v_max_f32_e32 v36, 0, v20
	v_mov_b32_e32 v20, v21
	v_mov_b32_e32 v21, v22
	v_mov_b32_e32 v22, v23
	v_fma_mixlo_f16 v23, v36, v36, 0
	v_max_f32_e32 v20, 0, v20
	v_max_f32_e32 v21, 0, v21
	v_max_f32_e32 v22, 0, v22
	v_pk_mul_f32 v[20:21], v[20:21], v[20:21]
	v_fma_mixlo_f16 v22, v22, v22, 0
	v_cvt_pk_f16_f32 v21, v20, v21
	v_pack_b32_f16 v20, v23, v21
	v_alignbit_b32 v21, v22, v21, 16
	v_mov_b32_e32 v22, v24
	v_max_f32_e32 v24, 0, v22
	v_mov_b32_e32 v22, v25
	v_mov_b32_e32 v23, v26
	v_max_f32_e32 v22, 0, v22
	v_max_f32_e32 v23, 0, v23
	v_mov_b32_e32 v25, v27
	v_pk_mul_f32 v[22:23], v[22:23], v[22:23]
	v_max_f32_e32 v25, 0, v25
	v_fma_mixlo_f16 v24, v24, v24, 0
	v_cvt_pk_f16_f32 v23, v22, v23
	v_pack_b32_f16 v22, v24, v23
	v_fma_mixlo_f16 v24, v25, v25, 0
	v_alignbit_b32 v23, v24, v23, 16
	v_permlane32_swap_b32_e32 v20, v22
	s_nop 0
	v_permlane32_swap_b32_e32 v21, v23
	global_store_dwordx4 v[0:1], v[20:23], off
	s_nop 1
	v_mov_b32_e32 v2, v28
	v_mov_b32_e32 v20, v29
	v_mov_b32_e32 v21, v30
	v_max_f32_e32 v20, 0, v20
	v_max_f32_e32 v21, 0, v21
	v_max_f32_e32 v2, 0, v2
	v_mov_b32_e32 v22, v31
	v_pk_mul_f32 v[20:21], v[20:21], v[20:21]
	v_max_f32_e32 v22, 0, v22
	v_fma_mixlo_f16 v2, v2, v2, 0
	v_cvt_pk_f16_f32 v21, v20, v21
	v_pack_b32_f16 v20, v2, v21
	v_fma_mixlo_f16 v2, v22, v22, 0
	v_alignbit_b32 v21, v2, v21, 16
	v_mov_b32_e32 v2, v32
	v_mov_b32_e32 v22, v33
	v_mov_b32_e32 v23, v34
	v_max_f32_e32 v22, 0, v22
	v_max_f32_e32 v23, 0, v23
	v_max_f32_e32 v2, 0, v2
	v_mov_b32_e32 v24, v35
	v_pk_mul_f32 v[22:23], v[22:23], v[22:23]
	v_max_f32_e32 v24, 0, v24
	v_fma_mixlo_f16 v2, v2, v2, 0
	v_cvt_pk_f16_f32 v23, v22, v23
	v_pack_b32_f16 v22, v2, v23
	v_fma_mixlo_f16 v2, v24, v24, 0
	v_alignbit_b32 v23, v2, v23, 16
	v_permlane32_swap_b32_e32 v20, v22
	s_nop 0
	v_permlane32_swap_b32_e32 v21, v23
	global_store_dwordx4 v[0:1], v[20:23], off offset:32
	s_nop 1
	v_mov_b32_e32 v2, v4
	v_mov_b32_e32 v4, v5
	v_mov_b32_e32 v5, v6
	v_mov_b32_e32 v6, v7
	v_max_f32_e32 v4, 0, v4
	v_max_f32_e32 v5, 0, v5
	v_max_f32_e32 v2, 0, v2
	v_pk_mul_f32 v[4:5], v[4:5], v[4:5]
	v_max_f32_e32 v6, 0, v6
	v_fma_mixlo_f16 v2, v2, v2, 0
	v_cvt_pk_f16_f32 v5, v4, v5
	v_pack_b32_f16 v4, v2, v5
	v_fma_mixlo_f16 v2, v6, v6, 0
	v_alignbit_b32 v5, v2, v5, 16
	v_mov_b32_e32 v6, v9
	v_mov_b32_e32 v7, v10
	v_mov_b32_e32 v2, v8
	v_max_f32_e32 v6, 0, v6
	v_max_f32_e32 v7, 0, v7
	v_max_f32_e32 v2, 0, v2
	v_mov_b32_e32 v8, v11
	v_pk_mul_f32 v[6:7], v[6:7], v[6:7]
	v_max_f32_e32 v8, 0, v8
	v_fma_mixlo_f16 v2, v2, v2, 0
	v_cvt_pk_f16_f32 v7, v6, v7
	v_pack_b32_f16 v6, v2, v7
	v_fma_mixlo_f16 v2, v8, v8, 0
	v_alignbit_b32 v7, v2, v7, 16
	v_permlane32_swap_b32_e32 v4, v6
	s_nop 0
	v_permlane32_swap_b32_e32 v5, v7
	global_store_dwordx4 v[0:1], v[4:7], off offset:64
	s_nop 1
	v_mov_b32_e32 v2, v12
	v_mov_b32_e32 v4, v13
	v_mov_b32_e32 v5, v14
	v_max_f32_e32 v4, 0, v4
	v_max_f32_e32 v5, 0, v5
	v_max_f32_e32 v2, 0, v2
	v_mov_b32_e32 v6, v15
	v_pk_mul_f32 v[4:5], v[4:5], v[4:5]
	v_max_f32_e32 v6, 0, v6
	v_fma_mixlo_f16 v2, v2, v2, 0
	v_cvt_pk_f16_f32 v5, v4, v5
	v_pack_b32_f16 v4, v2, v5
	v_fma_mixlo_f16 v2, v6, v6, 0
	v_alignbit_b32 v5, v2, v5, 16
	v_mov_b32_e32 v2, v16
	v_mov_b32_e32 v6, v17
	v_mov_b32_e32 v7, v18
	v_max_f32_e32 v6, 0, v6
	v_max_f32_e32 v7, 0, v7
	v_max_f32_e32 v2, 0, v2
	v_mov_b32_e32 v8, v19
	v_pk_mul_f32 v[6:7], v[6:7], v[6:7]
	v_max_f32_e32 v8, 0, v8
	v_fma_mixlo_f16 v2, v2, v2, 0
	v_cvt_pk_f16_f32 v7, v6, v7
	v_pack_b32_f16 v6, v2, v7
	v_fma_mixlo_f16 v2, v8, v8, 0
	v_alignbit_b32 v7, v2, v7, 16
	v_permlane32_swap_b32_e32 v4, v6
	s_nop 0
	v_permlane32_swap_b32_e32 v5, v7
	global_store_dwordx4 v[0:1], v[4:7], off offset:96
	s_nop 1
	s_cbranch_scc1 .LBB0_780

.LBB0_729:
	v_mov_b32_e32 v0, v200
	s_lshl_b32 s30, s52, 4
	v_ashrrev_i32_e32 v7, 6, v0
	v_lshrrev_b32_e32 v1, 4, v0
	v_bfe_u32 v4, v0, 2, 4
	v_xor_b32_e32 v1, v1, v0
	v_lshlrev_b32_e32 v5, 5, v7
	s_sub_i32 s30, s54, s30
	v_or_b32_e32 v12, v5, v4
	v_lshlrev_b32_e32 v1, 4, v1
	v_and_b32_e32 v6, 63, v0
	v_and_b32_e32 v2, 48, v1
	v_or_b32_e32 v1, 16, v12
	s_lshl_b32 s30, s30, 8
	v_bfe_u32 v176, v200, 6, 2
	v_bfe_u32 v177, v200, 5, 1
	v_lshlrev_b32_e32 v176, 6, v176
	v_lshl_or_b32 v176, v177, 2, v176
	v_add_u32_e32 v176, s30, v176
	v_lshlrev_b32_e32 v176, 2, v176
	global_load_dwordx4 v[144:147], v176, s[24:25]
	global_load_dwordx4 v[148:151], v176, s[24:25] offset:32
	global_load_dwordx4 v[152:155], v176, s[24:25] offset:64
	global_load_dwordx4 v[156:159], v176, s[24:25] offset:96
	global_load_dwordx4 v[160:163], v176, s[24:25] offset:128
	global_load_dwordx4 v[164:167], v176, s[24:25] offset:160
	global_load_dwordx4 v[168:171], v176, s[24:25] offset:192
	global_load_dwordx4 v[172:175], v176, s[24:25] offset:224
	v_add_u32_e32 v8, s36, v12
	v_add_u32_e32 v10, s36, v1
	v_add_u32_e32 v14, s30, v1
	v_lshlrev_b32_e32 v1, 4, v6
	v_ashrrev_i32_e32 v9, 31, v8
	v_lshl_or_b32 v1, v7, 11, v1
	v_lshlrev_b64 v[8:9], 11, v[8:9]
	v_ashrrev_i32_e32 v11, 31, v10
	v_add_u32_e32 v12, s30, v12
	v_add_u32_e32 v18, 16, v1
	v_lshl_add_u64 v[8:9], s[42:43], 0, v[8:9]
	v_lshlrev_b64 v[10:11], 11, v[10:11]
	v_ashrrev_i32_e32 v13, 31, v12
	v_readfirstlane_b32 s31, v18
	v_add_u32_e32 v16, 0x400, v18
	v_lshl_add_u64 v[8:9], v[8:9], 0, v[2:3]
	v_lshl_add_u64 v[10:11], s[42:43], 0, v[10:11]
	v_lshlrev_b64 v[12:13], 11, v[12:13]
	v_ashrrev_i32_e32 v15, 31, v14
	s_mov_b32 m0, s31
	v_readfirstlane_b32 s31, v16
	v_add_u32_e32 v16, 0x4000, v18
	v_lshl_add_u64 v[10:11], v[10:11], 0, v[2:3]
	v_lshl_add_u64 v[12:13], s[44:45], 0, v[12:13]
	v_lshlrev_b64 v[14:15], 11, v[14:15]
	global_load_lds_dwordx4 v[8:9], off
	s_mov_b32 m0, s31
	v_readfirstlane_b32 s31, v16
	v_add_u32_e32 v16, 0x4400, v18
	v_lshl_add_u64 v[12:13], v[12:13], 0, v[2:3]
	v_lshl_add_u64 v[14:15], s[44:45], 0, v[14:15]
	global_load_lds_dwordx4 v[10:11], off
	s_mov_b32 m0, s31
	v_readfirstlane_b32 s31, v16
	v_add_u32_e32 v19, 0x8000, v18
	v_lshl_add_u64 v[14:15], v[14:15], 0, v[2:3]
	global_load_lds_dwordx4 v[12:13], off
	s_mov_b32 m0, s31
	v_readfirstlane_b32 s31, v19
	v_add_u32_e32 v19, 0x8400, v18
	global_load_lds_dwordx4 v[14:15], off
	v_lshl_add_u64 v[16:17], v[8:9], 0, 64
	s_mov_b32 m0, s31
	v_readfirstlane_b32 s31, v19
	v_add_u32_e32 v19, 0xc000, v18
	global_load_lds_dwordx4 v[16:17], off
	v_lshl_add_u64 v[16:17], v[10:11], 0, 64
	s_mov_b32 m0, s31
	v_readfirstlane_b32 s31, v19
	v_add_u32_e32 v18, 0xc400, v18
	global_load_lds_dwordx4 v[16:17], off
	v_lshl_add_u64 v[16:17], v[12:13], 0, 64
	s_mov_b32 m0, s31
	v_readfirstlane_b32 s31, v18
	global_load_lds_dwordx4 v[16:17], off
	v_lshl_add_u64 v[16:17], v[14:15], 0, 64
	s_mov_b32 m0, s31
	s_add_i32 s31, 16, 0x10000
	global_load_lds_dwordx4 v[16:17], off
	v_add_u32_e32 v16, s31, v1
	v_lshl_add_u64 v[8:9], v[8:9], 0, s[92:93]
	v_readfirstlane_b32 s31, v16
	s_mov_b32 m0, s31
	s_nop 0
	global_load_lds_dwordx4 v[8:9], off
	v_lshl_add_u64 v[8:9], v[10:11], 0, s[92:93]
	v_add_u32_e32 v10, 0x400, v16
	s_nop 0
	v_readfirstlane_b32 s31, v10
	v_add_u32_e32 v10, 0x4000, v16
	s_mov_b32 m0, s31
	v_readfirstlane_b32 s31, v10
	v_add_u32_e32 v10, 0x4400, v16
	global_load_lds_dwordx4 v[8:9], off
	v_lshl_add_u64 v[8:9], v[12:13], 0, s[92:93]
	s_mov_b32 m0, s31
	v_readfirstlane_b32 s31, v10
	global_load_lds_dwordx4 v[8:9], off
	v_lshl_add_u64 v[8:9], v[14:15], 0, s[92:93]
	s_mov_b32 m0, s31
	v_readfirstlane_b32 s31, v0
	global_load_lds_dwordx4 v[8:9], off
	s_waitcnt vmcnt(8)
	s_and_b32 s37, s31, 0xffffff00
	s_cmpk_lg_i32 s37, 0x100
	s_barrier
	s_cbranch_scc1 .LBB0_731
	s_barrier
.LBB0_731:
	v_lshrrev_b32_e32 v8, 30, v7
	v_add_u32_e32 v8, v7, v8
	v_ashrrev_i32_e32 v8, 2, v8
	v_mul_i32_i24_e32 v9, 4, v8
	v_lshrrev_b32_e32 v182, 5, v6
	v_lshrrev_b32_e32 v6, 2, v0
	v_sub_u32_e32 v7, v7, v9
	v_and_b32_e32 v9, 31, v0
	v_bfe_u32 v10, v0, 2, 2
	v_bitop3_b32 v6, v182, v6, 3 bitop3:0x78
	v_lshl_or_b32 v0, v8, 7, v9
	v_lshlrev_b32_e32 v193, 4, v6
	v_bitop3_b32 v6, v182, v10, 2 bitop3:0x36
	v_or_b32_e32 v8, 16, v4
	s_lshl_b32 s37, s54, 8
	v_lshlrev_b32_e32 v194, 4, v6
	v_or_b32_e32 v6, s37, v8
	v_lshlrev_b32_e32 v180, 6, v7
	v_add_u32_e32 v6, v6, v5
	s_lshl_b32 s52, s52, 12
	v_or_b32_e32 v7, v180, v9
	v_subrev_u32_e32 v6, s52, v6
	v_lshlrev_b32_e32 v192, 6, v7
	v_ashrrev_i32_e32 v7, 31, v6
	v_lshlrev_b64 v[6:7], 11, v[6:7]
	v_or_b32_e32 v6, v6, v2
	v_lshl_add_u64 v[184:185], s[48:49], 0, v[6:7]
	v_or_b32_e32 v6, s37, v4
	v_add_u32_e32 v6, v6, v5
	v_subrev_u32_e32 v6, s52, v6
	v_ashrrev_i32_e32 v7, 31, v6
	v_lshlrev_b64 v[6:7], 11, v[6:7]
	v_or_b32_e32 v6, v6, v2
	v_lshl_add_u64 v[186:187], s[48:49], 0, v[6:7]
	v_add3_u32 v6, v8, s36, v5
	v_add3_u32 v4, v4, s36, v5
	v_ashrrev_i32_e32 v7, 31, v6
	v_ashrrev_i32_e32 v5, 31, v4
	v_lshlrev_b64 v[6:7], 11, v[6:7]
	v_lshlrev_b64 v[4:5], 11, v[4:5]
	v_or_b32_e32 v6, v6, v2
	v_or_b32_e32 v4, v4, v2
	v_mov_b32_e32 v116, v144
	v_lshlrev_b32_e32 v181, 6, v0
	v_lshl_add_u64 v[188:189], s[50:51], 0, v[6:7]
	v_lshl_add_u64 v[190:191], s[50:51], 0, v[4:5]
	s_mov_b32 s55, 0x18000
	s_mov_b32 s56, 0
	s_mov_b64 s[36:37], 0
	s_mov_b32 s57, 0
	v_mov_b32_e32 v117, v145
	v_mov_b32_e32 v118, v146
	v_mov_b32_e32 v119, v147
	v_mov_b32_e32 v120, v148
	v_mov_b32_e32 v121, v149
	v_mov_b32_e32 v122, v150
	v_mov_b32_e32 v123, v151
	v_mov_b32_e32 v124, v152
	v_mov_b32_e32 v125, v153
	v_mov_b32_e32 v126, v154
	v_mov_b32_e32 v127, v155
	v_mov_b32_e32 v128, v156
	v_mov_b32_e32 v129, v157
	v_mov_b32_e32 v130, v158
	v_mov_b32_e32 v131, v159
	v_mov_b32_e32 v100, v160
	v_mov_b32_e32 v101, v161
	v_mov_b32_e32 v102, v162
	v_mov_b32_e32 v103, v163
	v_mov_b32_e32 v104, v164
	v_mov_b32_e32 v105, v165
	v_mov_b32_e32 v106, v166
	v_mov_b32_e32 v107, v167
	v_mov_b32_e32 v108, v168
	v_mov_b32_e32 v109, v169
	v_mov_b32_e32 v110, v170
	v_mov_b32_e32 v111, v171
	v_mov_b32_e32 v112, v172
	v_mov_b32_e32 v113, v173
	v_mov_b32_e32 v114, v174
	v_mov_b32_e32 v115, v175
	v_mov_b32_e32 v84, v144
	v_mov_b32_e32 v85, v145
	v_mov_b32_e32 v86, v146
	v_mov_b32_e32 v87, v147
	v_mov_b32_e32 v88, v148
	v_mov_b32_e32 v89, v149
	v_mov_b32_e32 v90, v150
	v_mov_b32_e32 v91, v151
	v_mov_b32_e32 v92, v152
	v_mov_b32_e32 v93, v153
	v_mov_b32_e32 v94, v154
	v_mov_b32_e32 v95, v155
	v_mov_b32_e32 v96, v156
	v_mov_b32_e32 v97, v157
	v_mov_b32_e32 v98, v158
	v_mov_b32_e32 v99, v159
	v_mov_b32_e32 v68, v160
	v_mov_b32_e32 v69, v161
	v_mov_b32_e32 v70, v162
	v_mov_b32_e32 v71, v163
	v_mov_b32_e32 v72, v164
	v_mov_b32_e32 v73, v165
	v_mov_b32_e32 v74, v166
	v_mov_b32_e32 v75, v167
	v_mov_b32_e32 v76, v168
	v_mov_b32_e32 v77, v169
	v_mov_b32_e32 v78, v170
	v_mov_b32_e32 v79, v171
	v_mov_b32_e32 v80, v172
	v_mov_b32_e32 v81, v173
	v_mov_b32_e32 v82, v174
	v_mov_b32_e32 v83, v175
	v_mov_b32_e32 v52, v144
	v_mov_b32_e32 v53, v145
	v_mov_b32_e32 v54, v146
	v_mov_b32_e32 v55, v147
	v_mov_b32_e32 v56, v148
	v_mov_b32_e32 v57, v149
	v_mov_b32_e32 v58, v150
	v_mov_b32_e32 v59, v151
	v_mov_b32_e32 v60, v152
	v_mov_b32_e32 v61, v153
	v_mov_b32_e32 v62, v154
	v_mov_b32_e32 v63, v155
	v_mov_b32_e32 v64, v156
	v_mov_b32_e32 v65, v157
	v_mov_b32_e32 v66, v158
	v_mov_b32_e32 v67, v159
	v_mov_b32_e32 v36, v160
	v_mov_b32_e32 v37, v161
	v_mov_b32_e32 v38, v162
	v_mov_b32_e32 v39, v163
	v_mov_b32_e32 v40, v164
	v_mov_b32_e32 v41, v165
	v_mov_b32_e32 v42, v166
	v_mov_b32_e32 v43, v167
	v_mov_b32_e32 v44, v168
	v_mov_b32_e32 v45, v169
	v_mov_b32_e32 v46, v170
	v_mov_b32_e32 v47, v171
	v_mov_b32_e32 v48, v172
	v_mov_b32_e32 v49, v173
	v_mov_b32_e32 v50, v174
	v_mov_b32_e32 v51, v175
	v_mov_b32_e32 v20, v144
	v_mov_b32_e32 v21, v145
	v_mov_b32_e32 v22, v146
	v_mov_b32_e32 v23, v147
	v_mov_b32_e32 v24, v148
	v_mov_b32_e32 v25, v149
	v_mov_b32_e32 v26, v150
	v_mov_b32_e32 v27, v151
	v_mov_b32_e32 v28, v152
	v_mov_b32_e32 v29, v153
	v_mov_b32_e32 v30, v154
	v_mov_b32_e32 v31, v155
	v_mov_b32_e32 v32, v156
	v_mov_b32_e32 v33, v157
	v_mov_b32_e32 v34, v158
	v_mov_b32_e32 v35, v159
	v_mov_b32_e32 v4, v160
	v_mov_b32_e32 v5, v161
	v_mov_b32_e32 v6, v162
	v_mov_b32_e32 v7, v163
	v_mov_b32_e32 v8, v164
	v_mov_b32_e32 v9, v165
	v_mov_b32_e32 v10, v166
	v_mov_b32_e32 v11, v167
	v_mov_b32_e32 v12, v168
	v_mov_b32_e32 v13, v169
	v_mov_b32_e32 v14, v170
	v_mov_b32_e32 v15, v171
	v_mov_b32_e32 v16, v172
	v_mov_b32_e32 v17, v173
	v_mov_b32_e32 v18, v174
	v_mov_b32_e32 v19, v175
	s_branch .LBB0_733
